# split grid barrier between NSA selection and attention: arrive after selection, wait+acquire only before the NSA item class
# speedup vs baseline: 1.0141x; 1.0023x over previous
; __device__ __forceinline__ unsigned xb_ld(unsigned* p)              { return __hip_atomic_load(p, __ATOMIC_RELAXED, __HIP_MEMORY_SCOPE_AGENT); }
; __device__ __forceinline__ unsigned xb_add(unsigned* p, unsigned v) { return __hip_atomic_fetch_add(p, v, __ATOMIC_RELAXED, __HIP_MEMORY_SCOPE_AGENT); }
; #define XB_SPIN(cond, bar) do { unsigned _sp = 0; while (cond) { __builtin_amdgcn_s_sleep(1); \
;     if ((++_sp & 255u) == 0u) { if (xb_ld(&(bar)[XB_TMO])) break; if (_sp > XB_SPIN_CAP) { atomicAdd(&(bar)[XB_TMO], 1u); break; } } } } while (0)
; __device__ __forceinline__ void xcd_barrier(const XcdBarrier& b) {
;     ...
;         const unsigned old = xb_add(&bar[XB_XSUB(b.x)], 1u);
;         const unsigned gen = old / nloc;
;         if (old + 1u == (gen + 1u) * nloc) {
;             __builtin_amdgcn_fence(__ATOMIC_RELEASE, "agent");
;             asm volatile("s_waitcnt vmcnt(0)" ::: "memory");
;             const unsigned og = xb_add(&bar[XB_TOP], 1u);
;             const unsigned tg = og / nx;
;             if (og + 1u == (tg + 1u) * nx) xb_add(&bar[XB_TOPGEN], 1u);
;             else XB_SPIN(xb_ld(&bar[XB_TOPGEN]) == tg, bar);
;             __builtin_amdgcn_fence(__ATOMIC_ACQUIRE, "agent");
;             xb_add(&bar[XB_XGEN(b.x)], 1u);
;             asm volatile("s_waitcnt vmcnt(0)" ::: "memory");
;         } else {
;             XB_SPIN(xb_ld(&bar[XB_XGEN(b.x)]) == gen, bar);
.LBB0_514:
	v_readlane_b32 s6, v255, 3
	v_readlane_b32 s7, v255, 4
	v_mov_b32_e32 v1, 1
	s_nop 0
	v_mov_b64_e32 v[6:7], s[6:7]
	flat_atomic_add v5, v[6:7], v1 sc0
	v_cvt_f32_u32_e32 v1, v4
	v_sub_u32_e32 v6, 0, v4
	v_rcp_iflag_f32_e32 v1, v1
	s_nop 0
	v_mul_f32_e32 v1, 0x4f7ffffe, v1
	v_cvt_u32_f32_e32 v1, v1
	v_mul_lo_u32 v6, v6, v1
	v_mul_hi_u32 v6, v1, v6
	v_add_u32_e32 v1, v1, v6
	s_waitcnt vmcnt(0) lgkmcnt(0)
	v_mul_hi_u32 v1, v5, v1
	v_mul_lo_u32 v6, v1, v4
	v_sub_u32_e32 v6, v5, v6
	v_cmp_ge_u32_e32 vcc, v6, v4
	v_add_u32_e32 v7, 1, v1
	s_nop 0
	v_cndmask_b32_e32 v1, v1, v7, vcc
	v_sub_u32_e32 v7, v6, v4
	v_cndmask_b32_e32 v6, v6, v7, vcc
	v_cmp_ge_u32_e32 vcc, v6, v4
	v_add_u32_e32 v6, 1, v1
	s_nop 0
	v_cndmask_b32_e32 v1, v1, v6, vcc
	v_add_u32_e32 v6, 1, v5
	v_mad_u64_u32 v[4:5], s[6:7], v4, v1, v[4:5]
	v_readfirstlane_b32 s5, v1
	s_nop 1
	v_writelane_b32 v255, s5, 34
	v_cmp_ne_u32_e32 vcc, v6, v4
	s_and_saveexec_b64 s[6:7], vcc
	s_xor_b64 s[16:17], exec, s[6:7]
	s_cbranch_execz .LBB0_527
	s_branch .LBB0_527
	buffer_inv sc1
	v_readlane_b32 s6, v255, 5
	v_readlane_b32 s7, v255, 6
	s_nop 1
	v_mov_b64_e32 v[4:5], s[6:7]
	flat_load_dword v2, v[4:5] sc1
	s_waitcnt vmcnt(0) lgkmcnt(0)
	v_cmp_eq_u32_e32 vcc, v2, v1
	s_and_saveexec_b64 s[20:21], vcc
	s_cbranch_execz .LBB0_526
	s_mov_b32 s5, 1
	s_mov_b64 s[22:23], 0
	s_branch .LBB0_518

; __device__ __forceinline__ unsigned xb_ld(unsigned* p)              { return __hip_atomic_load(p, __ATOMIC_RELAXED, __HIP_MEMORY_SCOPE_AGENT); }
; __device__ __forceinline__ unsigned xb_add(unsigned* p, unsigned v) { return __hip_atomic_fetch_add(p, v, __ATOMIC_RELAXED, __HIP_MEMORY_SCOPE_AGENT); }
; #define XB_SPIN(cond, bar) do { unsigned _sp = 0; while (cond) { __builtin_amdgcn_s_sleep(1); \
;     if ((++_sp & 255u) == 0u) { if (xb_ld(&(bar)[XB_TMO])) break; if (_sp > XB_SPIN_CAP) { atomicAdd(&(bar)[XB_TMO], 1u); break; } } } } while (0)
; __device__ __forceinline__ void xcd_barrier(const XcdBarrier& b) {
;     ...
;         if (old + 1u == (gen + 1u) * nloc) {
;             __builtin_amdgcn_fence(__ATOMIC_RELEASE, "agent");
;             asm volatile("s_waitcnt vmcnt(0)" ::: "memory");
;             const unsigned og = xb_add(&bar[XB_TOP], 1u);
;             const unsigned tg = og / nx;
;             if (og + 1u == (tg + 1u) * nx) xb_add(&bar[XB_TOPGEN], 1u);
;             else XB_SPIN(xb_ld(&bar[XB_TOPGEN]) == tg, bar);
;             __builtin_amdgcn_fence(__ATOMIC_ACQUIRE, "agent");
;             xb_add(&bar[XB_XGEN(b.x)], 1u);
.LBB0_527:
	s_andn2_saveexec_b64 s[6:7], s[16:17]
	s_cbranch_execz .LBB0_543
	v_readlane_b32 s6, v255, 7
	v_readlane_b32 s7, v255, 8
	buffer_wbl2 sc1
	s_waitcnt vmcnt(0)
	v_mov_b32_e32 v1, 1
	v_mov_b64_e32 v[4:5], s[6:7]
	flat_atomic_add v4, v[4:5], v1 sc0
	v_cvt_f32_u32_e32 v1, v2
	v_sub_u32_e32 v5, 0, v2
	s_mov_b64 s[20:21], -1
	v_rcp_iflag_f32_e32 v1, v1
	s_nop 0
	v_mul_f32_e32 v1, 0x4f7ffffe, v1
	v_cvt_u32_f32_e32 v1, v1
	v_mul_lo_u32 v5, v5, v1
	v_mul_hi_u32 v5, v1, v5
	v_add_u32_e32 v1, v1, v5
	s_waitcnt vmcnt(0) lgkmcnt(0)
	v_mul_hi_u32 v1, v4, v1
	v_mul_lo_u32 v5, v1, v2
	v_sub_u32_e32 v5, v4, v5
	v_cmp_ge_u32_e32 vcc, v5, v2
	v_add_u32_e32 v6, 1, v1
	s_nop 0
	v_cndmask_b32_e32 v1, v1, v6, vcc
	v_sub_u32_e32 v6, v5, v2
	v_cndmask_b32_e32 v5, v5, v6, vcc
	v_cmp_ge_u32_e32 vcc, v5, v2
	v_add_u32_e32 v5, 1, v1
	v_add_u32_e32 v6, 1, v4
	v_cndmask_b32_e32 v1, v1, v5, vcc
	v_mad_u64_u32 v[4:5], s[6:7], v2, v1, v[2:3]
	v_readlane_b32 s6, v255, 9
	v_readlane_b32 s7, v255, 10
	v_cmp_ne_u32_e32 vcc, v6, v4
	s_nop 0
	v_mov_b64_e32 v[4:5], s[6:7]
	s_and_saveexec_b64 s[16:17], vcc
	s_cbranch_execz .LBB0_540
	s_mov_b64 s[20:21], 0
	s_branch .LBB0_540
	v_readlane_b32 s6, v255, 9
	v_readlane_b32 s7, v255, 10
	s_mov_b64 s[22:23], 0
	s_nop 0
	v_mov_b64_e32 v[4:5], s[6:7]
	flat_load_dword v2, v[4:5] sc1
	s_waitcnt vmcnt(0) lgkmcnt(0)
	v_cmp_eq_u32_e32 vcc, v2, v1
	s_and_saveexec_b64 s[20:21], vcc
	s_cbranch_execz .LBB0_539
	s_mov_b32 s5, 1
	s_branch .LBB0_532

; #define LAS __attribute__((address_space(3)))
; __device__ __forceinline__ unsigned xb_ld(unsigned* p)              { return __hip_atomic_load(p, __ATOMIC_RELAXED, __HIP_MEMORY_SCOPE_AGENT); }
; #define XB_SPIN(cond, bar) do { unsigned _sp = 0; while (cond) { __builtin_amdgcn_s_sleep(1); \
;     if ((++_sp & 255u) == 0u) { if (xb_ld(&(bar)[XB_TMO])) break; if (_sp > XB_SPIN_CAP) { atomicAdd(&(bar)[XB_TMO], 1u); break; } } } } while (0)
; __device__ __forceinline__ int fresh_lane() { int l = (int)__builtin_amdgcn_mbcnt_hi(~0u, __builtin_amdgcn_mbcnt_lo(~0u, 0u)); asm volatile("" : "+v"(l)); return l; }
; __device__ __forceinline__ void xcd_barrier(const XcdBarrier& b) {
;     ...
;             XB_SPIN(xb_ld(&bar[XB_XGEN(b.x)]) == gen, bar);
;             __builtin_amdgcn_fence(__ATOMIC_ACQUIRE, "agent");
; __device__ __forceinline__ void nsa_quad_item(const bf16* PROJ, const bf16* KC, const unsigned char* VCB, const unsigned char* VTB, const unsigned long long* SEL, bf16* O, LAS unsigned char* lds, int bg, int jp, int wave) {
;     const int lane = fresh_lane();
;     const int b = bg >> 1, g = bg & 1, wi = wave & 3, qd = wave >> 2, hd = 4 * g + wi, qt = 2 * jp + qd, qto = 2 * jp + (qd ^ 1), q = lane & 31, hh = lane >> 5, t0 = qt * 32, tq = t0 + q, tmax = t0 + 31;
;     LAS unsigned char* ring = lds + qd * 65536;
.LBB0_668:
	s_and_saveexec_b64 s[14:15], s[70:71]
	s_cbranch_execz .Lmy_sb_join
	v_readlane_b32 s4, v255, 34
	v_readlane_b32 s6, v255, 9
	v_readlane_b32 s7, v255, 10
	s_mov_b32 s5, 0
	s_nop 1
	v_mov_b64_e32 v[6:7], s[6:7]
.Lmy_sb_poll:
	flat_load_dword v2, v[6:7] sc1
	s_waitcnt vmcnt(0) lgkmcnt(0)
	v_readfirstlane_b32 s8, v2
	s_sub_i32 s8, s8, s4
	s_cmp_gt_i32 s8, 0
	s_cbranch_scc1 .Lmy_sb_done
	s_sleep 1
	s_add_i32 s5, s5, 1
	s_cmp_lt_u32 s5, 0x8000
	s_cbranch_scc1 .Lmy_sb_poll
.Lmy_sb_done:
	buffer_inv sc1
	s_waitcnt vmcnt(0)
.Lmy_sb_join:
	s_or_b64 exec, exec, s[14:15]
	s_barrier
	v_writelane_b32 v255, s33, 25
	s_add_i32 s2, s33, 16
	v_writelane_b32 v255, s2, 26
	s_ashr_i32 s48, s94, 2
	s_and_b32 s3, s94, 3
	v_writelane_b32 v255, s94, 27
	s_xor_b32 s49, s48, 1
	s_lshl_b32 s2, s48, 16
	s_add_i32 s94, s2, 0
	v_writelane_b32 v255, s3, 28
	s_lshl_b32 s55, s3, 10
	s_add_i32 s2, s49, 0x7d
	s_and_b32 s51, s48, 1
	s_add_i32 s56, s94, s55
	v_writelane_b32 v255, s2, 29
	s_add_i32 s2, s48, 0x7d
	s_xor_b32 s52, s51, 1
	s_lshl_b32 s53, s3, 3
	s_mul_i32 s54, s3, 0x18000
	v_writelane_b32 v255, s2, 30
	s_mov_b32 s59, 0
	s_mov_b32 s101, 0
	s_mov_b64 s[42:43], 0
	s_add_i32 s60, s56, 0x5000
	s_add_i32 s61, s56, 0x7000
	s_add_i32 s62, s56, 0x9000
	s_add_i32 s63, s56, 0xb000
	s_branch .LBB0_670
